# sample attention: first-half key-tile loads issued one tile earlier (counted vmcnt at loop top)
# baseline (speedup 1.0000x reference)
; __device__ __forceinline__ int lau_v(int x) { asm volatile("" : "+v"(x)); return x; }
; __device__ __forceinline__ void unit(const bf16_t* __restrict__ Qs_bh  , const float* __restrict__ Clat  , const float* __restrict__ Ckpe  , const bf16_t* __restrict__ Kn  , ...
;   const int tid = wid * 64 + lane, qh = wid >> 2, cq = wid & 3, l15 = lane & 15, g4 = lane >> 4, r32 = lane & 31, hi = lane >> 5;
;   float* wsf = (float*)(lds + WSCR) + wid * 64; float* li_l = wsf; float* al_l = wsf + 32;
; #pragma unroll
;   for (int j = 0; j < 8; ++j) { const int c = lau_v(tid) + 512 * j, q = c >> 6, ch = c & 63;
;     *(bf16x8*)(lds + QIMG + (ch >> 4) * 16384 + off_b(q, ch & 15)) = *reinterpret_cast<const bf16x8*>(Qs_bh + (size_t)q * (HEADS * KVW) + ch * 8); }
.LBB0_1550:
	s_ashr_i32 s6, s44, 3
	s_ashr_i32 s7, s6, 31
	s_and_b32 s45, s44, 7
	s_lshl_b64 s[2:3], s[6:7], 9
	s_or_b32 s2, s2, s45
	s_mulk_i32 s3, 0x480
	s_mul_hi_u32 s14, s2, 0x480
	s_lshl_b64 s[0:1], s[6:7], 6
	s_add_i32 s3, s14, s3
	s_mulk_i32 s2, 0x480
	s_add_u32 s14, s22, s2
	s_addc_u32 s15, s23, s3
	v_mov_b32_e32 v8, v210
	v_mov_b64_e32 v[2:3], s[14:15]
	v_ashrrev_i32_e32 v9, 6, v8
	v_and_b32_e32 v0, 63, v8
	s_movk_i32 s16, 0x2400
	v_mad_i64_i32 v[4:5], s[2:3], v9, s16, v[2:3]
	v_lshlrev_b32_e32 v0, 4, v0
	v_lshl_add_u64 v[4:5], v[4:5], 0, v[0:1]
	global_load_dwordx4 v[4:7], v[4:5], off
	v_lshlrev_b32_e32 v12, 2, v9
	v_lshlrev_b32_e32 v0, 10, v8
	v_and_b32_e32 v8, 15, v8
	v_lshlrev_b32_e32 v11, 8, v9
	v_bfe_u32 v9, v9, 2, 2
	v_and_b32_e32 v12, 12, v12
	v_and_b32_e32 v0, 0xc000, v0
	v_bitop3_b32 v8, v12, v8, v9 bitop3:0x36
	v_add_u32_e32 v0, s55, v0
	v_lshlrev_b32_e32 v8, 4, v8
	v_mov_b32_e32 v10, v210
	v_add3_u32 v0, v0, v8, v11
	v_mov_b32_e32 v9, v210
	v_mov_b32_e32 v14, v210
	s_movk_i32 s19, 0x1200
	s_movk_i32 s18, 0x200
	v_mov_b32_e32 v16, v208
	s_movk_i32 s20, 0x220
	v_mov_b32_e32 v17, v208
	v_mov_b32_e32 v18, v208
	v_mov_b32_e32 v19, v208
	v_mov_b32_e32 v20, v210
	v_mov_b32_e32 v21, v210
	s_mov_b32 s46, 0
	v_mov_b32_e32 v223, 0
	v_mov_b32_e32 v217, 0xf149f2ca
	s_waitcnt vmcnt(0)
	ds_write_b128 v0, v[4:7]
	s_nop 0
	v_add_u32_e32 v0, 0x200, v10
	v_and_b32_e32 v4, 63, v10
	v_ashrrev_i32_e32 v8, 6, v0
	v_lshlrev_b32_e32 v0, 4, v4
	v_mad_i64_i32 v[4:5], s[2:3], v8, s16, v[2:3]
	v_lshl_add_u64 v[4:5], v[4:5], 0, v[0:1]
	global_load_dwordx4 v[4:7], v[4:5], off
	v_lshlrev_b32_e32 v12, 2, v8
	v_lshlrev_b32_e32 v0, 10, v10
	v_and_b32_e32 v10, 15, v10
	v_lshlrev_b32_e32 v11, 8, v8
	v_bfe_u32 v8, v8, 2, 2
	v_and_b32_e32 v12, 12, v12
	v_and_b32_e32 v0, 0xc000, v0
	v_bitop3_b32 v8, v12, v10, v8 bitop3:0x36
	v_add_u32_e32 v0, s55, v0
	v_lshlrev_b32_e32 v8, 4, v8
	v_add3_u32 v0, v0, v8, v11
	v_mov_b32_e32 v10, v210
	s_waitcnt vmcnt(0)
	ds_write_b128 v0, v[4:7]
	s_nop 0
	v_add_u32_e32 v0, 0x400, v9
	v_and_b32_e32 v4, 63, v9
	v_ashrrev_i32_e32 v8, 6, v0
	v_lshlrev_b32_e32 v0, 4, v4
	v_mad_i64_i32 v[4:5], s[2:3], v8, s16, v[2:3]
	v_lshl_add_u64 v[4:5], v[4:5], 0, v[0:1]
	global_load_dwordx4 v[4:7], v[4:5], off
	v_lshlrev_b32_e32 v12, 2, v8
	v_lshlrev_b32_e32 v0, 10, v9
	v_and_b32_e32 v9, 15, v9
	v_lshlrev_b32_e32 v11, 8, v8
	v_bfe_u32 v8, v8, 2, 2
	v_and_b32_e32 v12, 12, v12
	v_and_b32_e32 v0, 0xc000, v0
	v_bitop3_b32 v8, v12, v9, v8 bitop3:0x36
	v_add_u32_e32 v0, s55, v0
	v_lshlrev_b32_e32 v8, 4, v8
	v_add3_u32 v0, v0, v8, v11
	v_mov_b32_e32 v9, v210
	s_waitcnt vmcnt(0)
	ds_write_b128 v0, v[4:7]
	s_nop 0
	v_add_u32_e32 v0, 0x600, v10
	v_and_b32_e32 v4, 63, v10
	v_ashrrev_i32_e32 v8, 6, v0
	v_lshlrev_b32_e32 v0, 4, v4
	v_mad_i64_i32 v[4:5], s[2:3], v8, s16, v[2:3]
	v_lshl_add_u64 v[4:5], v[4:5], 0, v[0:1]
	global_load_dwordx4 v[4:7], v[4:5], off
	v_lshlrev_b32_e32 v12, 2, v8
	v_lshlrev_b32_e32 v0, 10, v10
	v_and_b32_e32 v10, 15, v10
	v_lshlrev_b32_e32 v11, 8, v8
	v_bfe_u32 v8, v8, 2, 2
	v_and_b32_e32 v12, 12, v12
	v_and_b32_e32 v0, 0xc000, v0
	v_bitop3_b32 v8, v12, v10, v8 bitop3:0x36
	v_add_u32_e32 v0, s55, v0
	v_lshlrev_b32_e32 v8, 4, v8
	v_add3_u32 v0, v0, v8, v11
	v_mov_b32_e32 v10, v210
	s_waitcnt vmcnt(0)
	ds_write_b128 v0, v[4:7]
	s_nop 0
	v_add_u32_e32 v0, 0x800, v9
	v_and_b32_e32 v4, 63, v9
	v_ashrrev_i32_e32 v8, 6, v0
	v_lshlrev_b32_e32 v0, 4, v4
	v_mad_i64_i32 v[4:5], s[2:3], v8, s16, v[2:3]
	v_lshl_add_u64 v[4:5], v[4:5], 0, v[0:1]
	global_load_dwordx4 v[4:7], v[4:5], off
	v_lshlrev_b32_e32 v12, 2, v8
	v_lshlrev_b32_e32 v0, 10, v9
	v_and_b32_e32 v9, 15, v9
	v_lshlrev_b32_e32 v11, 8, v8
	v_bfe_u32 v8, v8, 2, 2
	v_and_b32_e32 v12, 12, v12
	v_and_b32_e32 v0, 0xc000, v0
	v_bitop3_b32 v8, v12, v9, v8 bitop3:0x36
	v_add_u32_e32 v0, s55, v0
	v_lshlrev_b32_e32 v8, 4, v8
	v_add3_u32 v0, v0, v8, v11
	v_mov_b32_e32 v9, v210
	s_waitcnt vmcnt(0)
	ds_write_b128 v0, v[4:7]
	s_nop 0
	v_add_u32_e32 v0, 0xa00, v10
	v_and_b32_e32 v4, 63, v10
	v_ashrrev_i32_e32 v8, 6, v0
	v_lshlrev_b32_e32 v0, 4, v4
	v_mad_i64_i32 v[4:5], s[2:3], v8, s16, v[2:3]
	v_lshl_add_u64 v[4:5], v[4:5], 0, v[0:1]
	global_load_dwordx4 v[4:7], v[4:5], off
	v_lshlrev_b32_e32 v12, 2, v8
	v_lshlrev_b32_e32 v0, 10, v10
	v_and_b32_e32 v10, 15, v10
	v_lshlrev_b32_e32 v11, 8, v8
	v_bfe_u32 v8, v8, 2, 2
	v_and_b32_e32 v12, 12, v12
	v_and_b32_e32 v0, 0xc000, v0
	v_bitop3_b32 v8, v12, v10, v8 bitop3:0x36
	v_add_u32_e32 v0, s55, v0
	v_lshlrev_b32_e32 v8, 4, v8
	v_add3_u32 v0, v0, v8, v11
	s_waitcnt vmcnt(0)
	ds_write_b128 v0, v[4:7]
	s_nop 0
	v_add_u32_e32 v0, 0xc00, v9
	v_and_b32_e32 v4, 63, v9
	v_ashrrev_i32_e32 v8, 6, v0
	v_lshlrev_b32_e32 v0, 4, v4
	v_mad_i64_i32 v[4:5], s[2:3], v8, s16, v[2:3]
	v_lshl_add_u64 v[4:5], v[4:5], 0, v[0:1]
	global_load_dwordx4 v[4:7], v[4:5], off
	v_lshlrev_b32_e32 v11, 2, v8
	v_lshlrev_b32_e32 v0, 10, v9
	v_and_b32_e32 v9, 15, v9
	v_lshlrev_b32_e32 v10, 8, v8
	v_bfe_u32 v8, v8, 2, 2
	v_and_b32_e32 v11, 12, v11
	v_and_b32_e32 v0, 0xc000, v0
	v_bitop3_b32 v8, v11, v9, v8 bitop3:0x36
	v_add_u32_e32 v0, s55, v0
	v_lshlrev_b32_e32 v8, 4, v8
	v_add3_u32 v0, v0, v8, v10
	v_mov_b32_e32 v8, v1
	v_mov_b32_e32 v9, v1
	s_waitcnt vmcnt(0)
; __device__ __forceinline__ int lau_v(int x) { asm volatile("" : "+v"(x)); return x; }
; #define AS_CV1(j_) do { if ((j_) < PAST / 64) { _Pragma("unroll") for (int i_ = 0; i_ < N1; ++i_) cv[i_] = AS_CVL(r1a[i_], r1b[i_]); } \
;     else { _Pragma("unroll") for (int i_ = 0; i_ < N1; ++i_) cv[i_] = AS_BC(r1a[i_]); } } while (0)
; __device__ __forceinline__ void unit(const bf16_t* __restrict__ Qs_bh  , const float* __restrict__ Clat  , const float* __restrict__ Ckpe  , const bf16_t* __restrict__ Kn  , ...
;     ...
;     *(bf16x8*)(lds + QIMG + (ch >> 4) * 16384 + off_b(q, ch & 15)) = *reinterpret_cast<const bf16x8*>(Qs_bh + (size_t)q * (HEADS * KVW) + ch * 8); }
;   bf16x8 qpe[2][2];
; #pragma unroll
;   for (int sb = 0; sb < 2; ++sb)
; #pragma unroll
;     for (int s2 = 0; s2 < 2; ++s2) { const int lq = lau_v(lane); qpe[sb][s2] = *reinterpret_cast<const bf16x8*>(Qs_bh + (unsigned)((32 * qh + 16 * sb + (lq & 15)) * (HEADS * KVW) + KVR + 32 * s2 + 8 * (lq >> 4))); }
;   int kb0, qb0, xsh, kpb[2];
;   { const int ln2 = lau_v(lane), l15b = ln2 & 15, g4b = ln2 >> 4; const int krow_ = 16 * cq + l15b, qrow_ = 32 * qh + l15b, clo = 16 * (g4b ^ ((l15b >> 2) & 3));
;     kb0 = KIMG + 256 * krow_ + clo; qb0 = QIMG + 256 * qrow_ + clo; xsh = (l15b & 3) << 6;
; #pragma unroll
;     for (int s = 0; s < 2; ++s) kpb[s] = KPE + krow_ * 128 + 16 * ((4 * s + g4b) ^ (krow_ & 7)); }
;   int vb[2], q4s;
;   { const int blk = (lane >> 4) & 1, q4 = (lane & 15) >> 2, p4 = lane & 3, c0 = 2 * blk + (p4 >> 1);
;     q4s = q4 << 6;
; #pragma unroll
;     for (int t = 0; t < 2; ++t) vb[t] = (int)(uintptr_t)lds + KIMG + cq * 16384 + 256 * (8 * hi + 4 * t + q4) + 16 * (c0 ^ ((2 * hi + t) & 3)) + 8 * (p4 & 1); }
;   const int sxw = SX + (32 * qh + l15) * SXLD + (16 * cq + 4 * g4) * 4;
;   const int sxr = SX + (32 * qh + r32) * SXLD + (8 * hi) * 4;
;   constexpr int NT = (PAST + DECS) / 64;
;   constexpr int N1 = 4, N2 = 8 - N1;
;   bf16x8 cv[9]; f32x4 r1a[N1], r1b[N1], r2a[N2 + 1], r2b[N2 + 1];
;     ...
;   float m_reg = -1e30f, l_reg = 0.f; f32x16 o[4] = {};
;   AS_LD1(0); AS_LD2(0); AS_CV1(0);
	ds_write_b128 v0, v[4:7]
	v_mov_b32_e32 v5, v1
	v_add_u32_e32 v0, 0xe00, v14
	v_and_b32_e32 v4, 63, v14
	v_ashrrev_i32_e32 v15, 6, v0
	v_lshlrev_b32_e32 v0, 4, v4
	v_mad_i64_i32 v[2:3], s[2:3], v15, s16, v[2:3]
	v_lshl_add_u64 v[2:3], v[2:3], 0, v[0:1]
	global_load_dwordx4 v[10:13], v[2:3], off
	v_lshlrev_b32_e32 v24, 2, v15
	v_lshlrev_b32_e32 v22, 10, v14
	v_and_b32_e32 v14, 15, v14
	v_lshlrev_b32_e32 v23, 8, v15
	v_bfe_u32 v15, v15, 2, 2
	v_and_b32_e32 v24, 12, v24
	v_and_b32_e32 v22, 0xc000, v22
	v_bitop3_b32 v14, v24, v14, v15 bitop3:0x36
	v_add_u32_e32 v22, s55, v22
	v_lshlrev_b32_e32 v14, 4, v14
	v_mov_b32_e32 v0, v208
	v_add3_u32 v14, v22, v14, v23
	s_lshl_b64 s[2:3], s[6:7], 12
	s_add_u32 s2, s2, s12
	s_addc_u32 s3, s3, s13
	s_lshl_b64 s[16:17], s[2:3], 11
	s_add_u32 s16, s8, s16
	s_addc_u32 s17, s9, s17
	s_lshl_b64 s[2:3], s[2:3], 8
	s_add_u32 s2, s10, s2
	s_addc_u32 s3, s11, s3
	s_add_u32 s0, s0, 0x4000
	s_addc_u32 s1, s1, 0
	v_mov_b32_e32 v2, v1
	v_mov_b32_e32 v3, v1
	v_mov_b32_e32 v4, v1
	v_mov_b32_e32 v6, v1
	v_mov_b32_e32 v7, v1
	s_waitcnt vmcnt(0)
	ds_write_b128 v14, v[10:13]
	s_nop 0
	v_and_or_b32 v10, v0, 15, s31
	v_ashrrev_i32_e32 v0, 1, v0
	v_mul_lo_u32 v10, v10, s19
	v_and_b32_e32 v0, -8, v0
	v_add3_u32 v0, v0, v10, s18
	v_lshl_add_u64 v[10:11], v[0:1], 1, s[14:15]
	global_load_dwordx4 v[80:83], v[10:11], off
	s_nop 0
	v_and_or_b32 v0, v16, 15, s31
	v_ashrrev_i32_e32 v10, 1, v16
	v_mul_lo_u32 v0, v0, s19
	v_and_b32_e32 v10, -8, v10
	v_add3_u32 v0, v10, v0, s20
	v_lshl_add_u64 v[10:11], v[0:1], 1, s[14:15]
	global_load_dwordx4 v[84:87], v[10:11], off
	s_nop 0
	v_and_or_b32 v0, v17, 15, s33
	v_ashrrev_i32_e32 v10, 1, v17
	v_mul_lo_u32 v0, v0, s19
	v_and_b32_e32 v10, -8, v10
	v_add3_u32 v0, v10, v0, s18
	v_lshl_add_u64 v[10:11], v[0:1], 1, s[14:15]
	global_load_dwordx4 v[88:91], v[10:11], off
	s_nop 0
	v_and_or_b32 v0, v18, 15, s33
	v_ashrrev_i32_e32 v10, 1, v18
	v_mul_lo_u32 v0, v0, s19
	v_and_b32_e32 v10, -8, v10
	v_add3_u32 v0, v10, v0, s20
	v_lshl_add_u64 v[10:11], v[0:1], 1, s[14:15]
	global_load_dwordx4 v[92:95], v[10:11], off
	s_movk_i32 s14, 0xffc0
	v_lshlrev_b32_e32 v0, 5, v20
	v_add_u32_e32 v12, 0x4000, v0
	v_add_u32_e32 v13, 0x8000, v0
	global_load_dwordx4 v[100:103], v0, s[16:17]
	global_load_dwordx4 v[96:99], v0, s[16:17] offset:16
	global_load_dwordx4 v[112:115], v12, s[16:17]
	global_load_dwordx4 v[108:111], v12, s[16:17] offset:16
	v_add_u32_e32 v0, 0xc000, v0
	global_load_dwordx4 v[140:143], v13, s[16:17]
	global_load_dwordx4 v[120:123], v13, s[16:17] offset:16
	global_load_dwordx4 v[152:155], v0, s[16:17]
	global_load_dwordx4 v[132:135], v0, s[16:17] offset:16
	v_lshrrev_b32_e32 v17, 2, v19
	v_lshlrev_b32_e32 v13, 5, v21
	v_add_u32_e32 v14, 0x10000, v13
	v_add_u32_e32 v15, 0x14000, v13
	v_add_u32_e32 v16, 0x18000, v13
	v_add_u32_e32 v13, 0x1c000, v13
	global_load_dwordx4 v[104:107], v14, s[16:17] offset:16
	global_load_dwordx4 v[164:167], v14, s[16:17]
	global_load_dwordx4 v[116:119], v15, s[16:17] offset:16
	global_load_dwordx4 v[168:171], v15, s[16:17]
	global_load_dwordx4 v[128:131], v16, s[16:17] offset:16
	global_load_dwordx4 v[172:175], v16, s[16:17]
	global_load_dwordx4 v[144:147], v13, s[16:17] offset:16
	global_load_dwordx4 v[176:179], v13, s[16:17]
	v_lshlrev_b32_e32 v12, 2, v21
	v_lshlrev_b32_e32 v0, 3, v21
	v_and_b32_e32 v12, 28, v12
	v_and_or_b32 v0, v0, s14, v12
	v_lshl_add_u64 v[12:13], v[0:1], 2, s[2:3]
	global_load_dwordx4 v[180:183], v[12:13], off
	global_load_dwordx4 v[156:159], v[12:13], off offset:128
	s_mul_hi_u32 s2, s0, 0x480
	s_mul_i32 s16, s1, 0x480
	s_mul_i32 s3, s0, 0x480
	s_add_i32 s2, s2, s16
	s_add_u32 s16, s24, s3
	v_and_b32_e32 v0, 15, v19
	v_ashrrev_i32_e32 v16, 4, v19
	s_addc_u32 s17, s25, s2
	s_lshl_b64 s[2:3], s[6:7], 23
	v_or_b32_e32 v20, s34, v0
	v_bitop3_b32 v17, v17, v16, 3 bitop3:0x6c
	v_bitop3_b32 v21, v16, v19, 7 bitop3:0x78
	v_add_u32_e32 v16, 4, v16
	s_add_u32 s47, s42, s2
	v_lshlrev_b32_e32 v18, 6, v19
	v_or_b32_e32 v0, s31, v0
	v_bitop3_b32 v16, v16, v19, 7 bitop3:0x78
	v_lshl_add_u32 v17, v17, 4, s55
	v_lshl_add_u32 v19, v20, 7, s55
	v_mov_b32_e32 v14, v1
	v_mov_b32_e32 v15, v1
	s_addc_u32 s48, s43, s3
	s_lshl_b64 s[2:3], s[6:7], 20
	v_and_b32_e32 v218, 0xc0, v18
	v_lshlrev_b32_e32 v18, 8, v20
	v_lshlrev_b32_e32 v21, 4, v21
	v_lshlrev_b32_e32 v16, 4, v16
	v_lshl_add_u32 v220, v0, 8, v17
	v_add_u32_e32 v0, 0x20000, v19
	v_mov_b32_e32 v10, v1
	v_mov_b32_e32 v11, v1
	v_mov_b32_e32 v12, v1
	v_mov_b32_e32 v13, v1
	s_add_u32 s18, s36, s2
	v_add3_u32 v219, v17, v18, s65
	v_add_u32_e32 v221, v0, v16
	v_add_u32_e32 v222, v0, v21
	v_mov_b32_e32 v0, v1
	v_mov_b64_e32 v[30:31], v[14:15]
	v_mov_b64_e32 v[46:47], v[14:15]
	v_mov_b64_e32 v[62:63], v[14:15]
	v_mov_b64_e32 v[78:79], v[14:15]
	s_mov_b64 s[14:15], 0
	s_addc_u32 s19, s37, s3
	v_mov_b64_e32 v[28:29], v[12:13]
	v_mov_b64_e32 v[26:27], v[10:11]
	v_mov_b64_e32 v[24:25], v[8:9]
	v_mov_b64_e32 v[22:23], v[6:7]
	v_mov_b64_e32 v[20:21], v[4:5]
	v_mov_b64_e32 v[18:19], v[2:3]
	v_mov_b64_e32 v[16:17], v[0:1]
	v_mov_b64_e32 v[44:45], v[12:13]
	v_mov_b64_e32 v[42:43], v[10:11]
	v_mov_b64_e32 v[40:41], v[8:9]
	v_mov_b64_e32 v[38:39], v[6:7]
	v_mov_b64_e32 v[36:37], v[4:5]
	v_mov_b64_e32 v[34:35], v[2:3]
	v_mov_b64_e32 v[32:33], v[0:1]
	v_mov_b64_e32 v[60:61], v[12:13]
	v_mov_b64_e32 v[58:59], v[10:11]
	s_waitcnt vmcnt(17)
; #define AS_CV1(j_) do { if ((j_) < PAST / 64) { _Pragma("unroll") for (int i_ = 0; i_ < N1; ++i_) cv[i_] = AS_CVL(r1a[i_], r1b[i_]); } \
;     else { _Pragma("unroll") for (int i_ = 0; i_ < N1; ++i_) cv[i_] = AS_BC(r1a[i_]); } } while (0)
; __device__ __forceinline__ void unit(const bf16_t* __restrict__ Qs_bh  , const float* __restrict__ Clat  , const float* __restrict__ Ckpe  , const bf16_t* __restrict__ Kn  , ...
;     ...
;   float m_reg = -1e30f, l_reg = 0.f; f32x16 o[4] = {};
;   AS_LD1(0); AS_LD2(0); AS_CV1(0);
; #pragma unroll 1
;   for (int j = 0; j < NT; ++j) {
	v_cvt_pk_bf16_f32 v124, v100, v101
	v_cvt_pk_bf16_f32 v125, v102, v103
	s_waitcnt vmcnt(16)
	v_cvt_pk_bf16_f32 v126, v96, v97
	v_cvt_pk_bf16_f32 v127, v98, v99
	s_waitcnt vmcnt(15)
	v_cvt_pk_bf16_f32 v136, v112, v113
	v_cvt_pk_bf16_f32 v137, v114, v115
	s_waitcnt vmcnt(14)
	v_cvt_pk_bf16_f32 v138, v108, v109
	v_cvt_pk_bf16_f32 v139, v110, v111
	s_waitcnt vmcnt(13)
	v_cvt_pk_bf16_f32 v148, v140, v141
	v_cvt_pk_bf16_f32 v149, v142, v143
	s_waitcnt vmcnt(12)
	v_cvt_pk_bf16_f32 v150, v120, v121
	v_cvt_pk_bf16_f32 v151, v122, v123
	s_waitcnt vmcnt(11)
	v_cvt_pk_bf16_f32 v160, v152, v153
	v_cvt_pk_bf16_f32 v161, v154, v155
	s_waitcnt vmcnt(10)
	v_cvt_pk_bf16_f32 v162, v132, v133
	v_cvt_pk_bf16_f32 v163, v134, v135
	v_mov_b64_e32 v[56:57], v[8:9]
	v_mov_b64_e32 v[54:55], v[6:7]
	v_mov_b64_e32 v[52:53], v[4:5]
	v_mov_b64_e32 v[50:51], v[2:3]
	v_mov_b64_e32 v[48:49], v[0:1]
	v_mov_b64_e32 v[76:77], v[12:13]
	v_mov_b64_e32 v[74:75], v[10:11]
	v_mov_b64_e32 v[72:73], v[8:9]
	v_mov_b64_e32 v[70:71], v[6:7]
	v_mov_b64_e32 v[68:69], v[4:5]
	v_mov_b64_e32 v[66:67], v[2:3]
	v_mov_b64_e32 v[64:65], v[0:1]
	v_mov_b32_e32 v0, v210
	s_add_u32 s2, s47, s14
	v_lshlrev_b32_e32 v0, 5, v0
	s_addc_u32 s3, s48, s15
	v_lshl_add_u64 v[2:3], s[2:3], 0, v[0:1]
	v_lshl_add_u64 v[4:5], v[2:3], 0, s[76:77]
	v_add_co_u32_e32 v2, vcc, 0x20000, v2
	s_nop 1
	v_addc_co_u32_e32 v3, vcc, 0, v3, vcc
	global_load_dwordx4 v[100:103], v[2:3], off
	global_load_dwordx4 v[96:99], v[4:5], off offset:16
	v_add_u32_e32 v2, 0x4000, v0
	v_mov_b32_e32 v3, v1
	v_lshl_add_u64 v[2:3], s[2:3], 0, v[2:3]
	v_lshl_add_u64 v[4:5], v[2:3], 0, s[76:77]
	v_add_co_u32_e32 v2, vcc, s84, v2
	s_nop 1
	v_addc_co_u32_e32 v3, vcc, 0, v3, vcc
	global_load_dwordx4 v[112:115], v[2:3], off
	global_load_dwordx4 v[108:111], v[4:5], off offset:16
	v_add_u32_e32 v2, 0x8000, v0
	v_mov_b32_e32 v3, v1
	v_lshl_add_u64 v[2:3], s[2:3], 0, v[2:3]
	v_lshl_add_u64 v[4:5], v[2:3], 0, s[76:77]
	v_add_co_u32_e32 v2, vcc, s84, v2
	v_add_u32_e32 v0, 0xc000, v0
	s_nop 0
	v_addc_co_u32_e32 v3, vcc, 0, v3, vcc
	global_load_dwordx4 v[140:143], v[2:3], off
	global_load_dwordx4 v[120:123], v[4:5], off offset:16
	v_lshl_add_u64 v[2:3], s[2:3], 0, v[0:1]
	v_lshl_add_u64 v[4:5], v[2:3], 0, s[76:77]
	v_add_co_u32_e32 v2, vcc, 0x20000, v2
	s_nop 1
	v_addc_co_u32_e32 v3, vcc, 0, v3, vcc
	global_load_dwordx4 v[152:155], v[2:3], off
	global_load_dwordx4 v[132:135], v[4:5], off offset:16
.LBB0_1551:
	s_cmp_lt_u32 s46, 63
	s_cbranch_scc0 .Lsa_w_tail
	s_waitcnt vmcnt(8)
	s_branch .Lsa_w_done
.Lsa_w_tail:
	s_cmp_eq_u32 s46, 63
	s_cbranch_scc0 .Lsa_w_last
	s_waitcnt vmcnt(4)
	s_branch .Lsa_w_done

; __device__ __forceinline__ int lau_v(int x) { asm volatile("" : "+v"(x)); return x; }
; #define AS_CV1(j_) do { if ((j_) < PAST / 64) { _Pragma("unroll") for (int i_ = 0; i_ < N1; ++i_) cv[i_] = AS_CVL(r1a[i_], r1b[i_]); } \
;     else { _Pragma("unroll") for (int i_ = 0; i_ < N1; ++i_) cv[i_] = AS_BC(r1a[i_]); } } while (0)
; #define AS_CV2(j_) do { if ((j_) < PAST / 64) { _Pragma("unroll") for (int i_ = 0; i_ < N2; ++i_) cv[N1 + i_] = AS_CVL(r2a[i_], r2b[i_]); cv[8] = AS_CVP(r2a[N2], r2b[N2]); } \
;     else { _Pragma("unroll") for (int i_ = 0; i_ < N2; ++i_) cv[N1 + i_] = AS_BC(r2a[i_]); cv[8] = AS_BC(r2a[N2]); } } while (0)
; __device__ __forceinline__ void unit(const bf16_t* __restrict__ Qs_bh  , const float* __restrict__ Clat  , const float* __restrict__ Ckpe  , const bf16_t* __restrict__ Kn  , ...
;     ...
;   float m_reg = -1e30f, l_reg = 0.f; f32x16 o[4] = {};
;   AS_LD1(0); AS_LD2(0); AS_CV1(0);
; #pragma unroll 1
;   for (int j = 0; j < NT; ++j) {
;     AS_CV2(j);
;     __syncthreads();
;     { const int tl = lau_v(tid);
; #pragma unroll
;       for (int i = 0; i < 8; ++i) { const int c = tl + 512 * i, row = c >> 6, ch = c & 63; *(bf16x8*)(lds + KIMG + (ch >> 4) * 16384 + (int)off_b(row, ch & 15)) = cv[i]; }
;       { const int row = tl >> 3, cp = tl & 7; *(bf16x8*)(lds + KPE + row * 128 + 16 * (cp ^ (row & 7))) = cv[8]; } }
;     __syncthreads();
.Lsa_w_done:
	s_cmp_lg_u32 s14, 0x800000
	v_mov_b64_e32 v[190:191], v[182:183]
	v_mov_b64_e32 v[186:187], v[178:179]
	v_mov_b64_e32 v[10:11], v[172:173]
	v_mov_b64_e32 v[6:7], v[168:169]
	v_mov_b64_e32 v[2:3], v[164:165]
	s_cselect_b64 s[20:21], -1, 0
	s_cmp_eq_u32 s14, 0x800000
	v_mov_b64_e32 v[188:189], v[180:181]
	v_mov_b64_e32 v[184:185], v[176:177]
	v_mov_b64_e32 v[12:13], v[174:175]
	v_mov_b64_e32 v[8:9], v[170:171]
	v_mov_b64_e32 v[4:5], v[166:167]
	s_cbranch_scc1 .LBB0_1553
	v_cvt_pk_bf16_f32 v2, v164, v165
	v_cvt_pk_bf16_f32 v3, v166, v167
	v_cvt_pk_bf16_f32 v4, v104, v105
	v_cvt_pk_bf16_f32 v5, v106, v107
	v_cvt_pk_bf16_f32 v6, v168, v169
	v_cvt_pk_bf16_f32 v7, v170, v171
	v_cvt_pk_bf16_f32 v8, v116, v117
	v_cvt_pk_bf16_f32 v9, v118, v119
	v_cvt_pk_bf16_f32 v10, v172, v173
	v_cvt_pk_bf16_f32 v11, v174, v175
	v_cvt_pk_bf16_f32 v12, v128, v129
	v_cvt_pk_bf16_f32 v13, v130, v131
	v_cvt_pk_bf16_f32 v184, v176, v177
	v_cvt_pk_bf16_f32 v185, v178, v179
	v_cvt_pk_bf16_f32 v186, v144, v145
	v_cvt_pk_bf16_f32 v187, v146, v147
	v_cvt_pk_bf16_f32 v188, v180, v156
	v_cvt_pk_bf16_f32 v189, v181, v157
	v_cvt_pk_bf16_f32 v190, v182, v158
	v_cvt_pk_bf16_f32 v191, v183, v159
.LBB0_1553:
	v_mov_b32_e32 v0, v210
	s_waitcnt lgkmcnt(0)
	s_barrier
	s_andn2_b64 vcc, exec, s[20:21]
	v_ashrrev_i32_e32 v192, 6, v0
	v_lshlrev_b32_e32 v194, 2, v192
	v_lshlrev_b32_e32 v14, 10, v0
	v_and_b32_e32 v15, 15, v0
	v_lshlrev_b32_e32 v193, 8, v192
	v_and_b32_e32 v194, 12, v194
	v_bfe_u32 v192, v192, 2, 2
	v_and_b32_e32 v14, 0xc000, v14
	v_bitop3_b32 v192, v194, v15, v192 bitop3:0x36
	v_add_u32_e32 v14, s35, v14
	v_lshlrev_b32_e32 v192, 4, v192
	v_add3_u32 v192, v14, v192, v193
	ds_write_b128 v192, v[124:127]
	v_add_u32_e32 v192, 0x200, v0
	v_ashrrev_i32_e32 v192, 6, v192
	v_lshlrev_b32_e32 v194, 2, v192
	v_lshlrev_b32_e32 v193, 8, v192
	v_and_b32_e32 v194, 12, v194
	v_bfe_u32 v192, v192, 2, 2
	v_bitop3_b32 v192, v194, v15, v192 bitop3:0x36
	v_lshlrev_b32_e32 v192, 4, v192
	v_add3_u32 v192, v14, v192, v193
	ds_write_b128 v192, v[136:139]
	v_add_u32_e32 v192, 0x400, v0
	v_ashrrev_i32_e32 v192, 6, v192
	v_lshlrev_b32_e32 v194, 2, v192
	v_lshlrev_b32_e32 v193, 8, v192
	v_and_b32_e32 v194, 12, v194
	v_bfe_u32 v192, v192, 2, 2
	v_bitop3_b32 v192, v194, v15, v192 bitop3:0x36
	v_lshlrev_b32_e32 v192, 4, v192
	v_add3_u32 v192, v14, v192, v193
	ds_write_b128 v192, v[148:151]
	v_add_u32_e32 v192, 0x600, v0
	v_ashrrev_i32_e32 v192, 6, v192
	v_lshlrev_b32_e32 v194, 2, v192
	v_lshlrev_b32_e32 v193, 8, v192
	v_and_b32_e32 v194, 12, v194
	v_bfe_u32 v192, v192, 2, 2
	v_bitop3_b32 v192, v194, v15, v192 bitop3:0x36
	v_lshlrev_b32_e32 v192, 4, v192
	v_add3_u32 v192, v14, v192, v193
	ds_write_b128 v192, v[160:163]
	v_add_u32_e32 v192, 0x800, v0
	v_ashrrev_i32_e32 v192, 6, v192
	v_lshlrev_b32_e32 v194, 2, v192
	v_lshlrev_b32_e32 v193, 8, v192
	v_and_b32_e32 v194, 12, v194
	v_bfe_u32 v192, v192, 2, 2
	v_bitop3_b32 v192, v194, v15, v192 bitop3:0x36
	v_lshlrev_b32_e32 v192, 4, v192
	v_add3_u32 v192, v14, v192, v193
	ds_write_b128 v192, v[2:5]
	v_add_u32_e32 v2, 0xa00, v0
	v_ashrrev_i32_e32 v2, 6, v2
	v_lshlrev_b32_e32 v4, 2, v2
	v_lshlrev_b32_e32 v3, 8, v2
	v_and_b32_e32 v4, 12, v4
	v_bfe_u32 v2, v2, 2, 2
	v_bitop3_b32 v2, v4, v15, v2 bitop3:0x36
	v_lshlrev_b32_e32 v2, 4, v2
	v_add3_u32 v2, v14, v2, v3
	ds_write_b128 v2, v[6:9]
	v_add_u32_e32 v2, 0xc00, v0
	v_ashrrev_i32_e32 v2, 6, v2
	v_lshlrev_b32_e32 v4, 2, v2
	v_lshlrev_b32_e32 v3, 8, v2
	v_and_b32_e32 v4, 12, v4
	v_bfe_u32 v2, v2, 2, 2
	v_bitop3_b32 v2, v4, v15, v2 bitop3:0x36
	v_lshlrev_b32_e32 v2, 4, v2
	v_add3_u32 v2, v14, v2, v3
	ds_write_b128 v2, v[10:13]
	v_add_u32_e32 v2, 0xe00, v0
	v_ashrrev_i32_e32 v2, 6, v2
	v_lshlrev_b32_e32 v4, 2, v2
	v_lshlrev_b32_e32 v3, 8, v2
	v_and_b32_e32 v4, 12, v4
	v_bfe_u32 v2, v2, 2, 2
	v_bitop3_b32 v2, v4, v15, v2 bitop3:0x36
	v_lshlrev_b32_e32 v2, 4, v2
	v_add3_u32 v2, v14, v2, v3
	ds_write_b128 v2, v[184:187]
	v_ashrrev_i32_e32 v2, 3, v0
	v_xor_b32_e32 v0, v2, v0
	v_lshlrev_b32_e32 v0, 4, v0
	v_lshlrev_b32_e32 v3, 7, v2
	v_and_b32_e32 v0, 0x70, v0
	v_add3_u32 v0, s38, v3, v0
	ds_write_b128 v0, v[188:191]
	v_cndmask_b32_e64 v0, 0, 1, s[20:21]
	v_cmp_ne_u32_e64 s[6:7], 1, v0
	s_waitcnt lgkmcnt(0)
	s_barrier
; __device__ __forceinline__ int lau_v(int x) { asm volatile("" : "+v"(x)); return x; }
; #define AS_CV1(j_) do { if ((j_) < PAST / 64) { _Pragma("unroll") for (int i_ = 0; i_ < N1; ++i_) cv[i_] = AS_CVL(r1a[i_], r1b[i_]); } \
;     else { _Pragma("unroll") for (int i_ = 0; i_ < N1; ++i_) cv[i_] = AS_BC(r1a[i_]); } } while (0)
; #define AS_SLD(set, g_) do { _Pragma("unroll") for (int i_ = 0; i_ < 2; ++i_) { const int s_ = 2 * (g_) + i_; const int xs_ = (64 * (s_ & 3)) ^ xsl; \
;         fa[set][i_] = *(const bf16x8*)(lds + kb0 + xs_ + (s_ >> 2) * 16384); fb0[set][i_] = *(const bf16x8*)(lds + qb0 + xs_ + (s_ >> 2) * 16384); fb1[set][i_] = *(const bf16x8*)(lds + qb0 + xs_ + (s_ >> 2) * 16384 + 4096); } } while (0)
; __device__ __forceinline__ void unit(const bf16_t* __restrict__ Qs_bh  , const float* __restrict__ Clat  , const float* __restrict__ Ckpe  , const bf16_t* __restrict__ Kn  , ...
;     ...
;     if (j + 1 < NT) AS_LD1(j + 1);
;     f32x4 sa[2] = {{0.f, 0.f, 0.f, 0.f}, {0.f, 0.f, 0.f, 0.f}};
;     const int xsl = lau_v(xsh);
;     bf16x8 fa[2][2], fb0[2][2], fb1[2][2], fp[2];
;     ...
;     AS_SLD(0, 0);
; #pragma unroll
;     for (int g = 0; g < 8; ++g) {
;       if (g < 7) AS_SLD((g + 1) & 1, g + 1); else { fp[0] = *(const bf16x8*)(lds + kpb[0]); fp[1] = *(const bf16x8*)(lds + kpb[1]); }
;       __builtin_amdgcn_sched_barrier(0);
; #pragma unroll
;       for (int i = 0; i < 2; ++i) {
;         sa[0] = __builtin_amdgcn_mfma_f32_16x16x32_bf16(fa[g & 1][i], fb0[g & 1][i], sa[0], 0, 0, 0);
;         sa[1] = __builtin_amdgcn_mfma_f32_16x16x32_bf16(fa[g & 1][i], fb1[g & 1][i], sa[1], 0, 0, 0); }
;       __builtin_amdgcn_sched_barrier(0);
;     }
;     ...
; #pragma unroll
;     for (int s = 0; s < 2; ++s) {
;       sa[0] = __builtin_amdgcn_mfma_f32_16x16x32_bf16(fp[s], qpe[0][s], sa[0], 0, 0, 0);
;       sa[1] = __builtin_amdgcn_mfma_f32_16x16x32_bf16(fp[s], qpe[1][s], sa[1], 0, 0, 0); }
;     *(f32x4*)(lds + sxw) = sa[0]; *(f32x4*)(lds + sxw + 16 * SXLD) = sa[1];
;     __syncthreads();
;     if (j + 1 < NT) { AS_CV1(j + 1); AS_LD2(j + 1); }
.LBB0_1558:
	v_mov_b32_e32 v0, v218
	s_nop 0
	v_add_u32_e32 v14, v219, v0
	v_add_u32_e32 v15, v220, v0
	v_xor_b32_e32 v188, 64, v0
	v_xor_b32_e32 v196, 0x80, v0
	v_xor_b32_e32 v0, 0xc0, v0
	v_add_u32_e32 v225, v220, v188
	v_add_u32_e32 v238, v219, v196
	v_add_u32_e32 v239, v220, v196
	v_add_u32_e32 v240, v219, v0
	v_add_u32_e32 v0, v220, v0
	ds_read_b128 v[2:5], v14
	ds_read_b128 v[6:9], v15
	v_add_u32_e32 v224, v219, v188
	ds_read_b128 v[10:13], v15 offset:4096
	ds_read_b128 v[184:187], v224
	ds_read_b128 v[188:191], v225
	ds_read_b128 v[192:195], v225 offset:4096
	ds_read_b128 v[196:199], v238
	ds_read_b128 v[200:203], v239
	ds_read_b128 v[226:229], v239 offset:4096
	ds_read_b128 v[230:233], v240
	ds_read_b128 v[234:237], v0
	ds_read_b128 v[242:245], v0 offset:4096
	s_waitcnt lgkmcnt(10)
	v_mfma_f32_16x16x32_bf16 v[6:9], v[2:5], v[6:9], 0
	s_waitcnt lgkmcnt(9)
	v_mfma_f32_16x16x32_bf16 v[2:5], v[2:5], v[10:13], 0
	s_waitcnt lgkmcnt(7)
	v_mfma_f32_16x16x32_bf16 v[6:9], v[184:187], v[188:191], v[6:9]
	s_waitcnt lgkmcnt(6)
	v_mfma_f32_16x16x32_bf16 v[2:5], v[184:187], v[192:195], v[2:5]
	ds_read_b128 v[10:13], v14 offset:16384
	ds_read_b128 v[184:187], v15 offset:16384
	ds_read_b128 v[188:191], v15 offset:20480
	ds_read_b128 v[192:195], v224 offset:16384
	ds_read_b128 v[246:249], v225 offset:16384
	ds_read_b128 v[204:207], v225 offset:20480
	s_waitcnt lgkmcnt(10)
	v_mfma_f32_16x16x32_bf16 v[6:9], v[196:199], v[200:203], v[6:9]
	s_waitcnt lgkmcnt(9)
	v_mfma_f32_16x16x32_bf16 v[2:5], v[196:199], v[226:229], v[2:5]
	s_waitcnt lgkmcnt(7)
	v_mfma_f32_16x16x32_bf16 v[6:9], v[230:233], v[234:237], v[6:9]
	s_waitcnt lgkmcnt(6)
	v_mfma_f32_16x16x32_bf16 v[2:5], v[230:233], v[242:245], v[2:5]
	ds_read_b128 v[196:199], v238 offset:16384
	ds_read_b128 v[200:203], v239 offset:16384
	ds_read_b128 v[226:229], v239 offset:20480
	ds_read_b128 v[230:233], v240 offset:16384
	ds_read_b128 v[234:237], v0 offset:16384
	ds_read_b128 v[242:245], v0 offset:20480
	s_waitcnt lgkmcnt(10)
	v_mfma_f32_16x16x32_bf16 v[6:9], v[10:13], v[184:187], v[6:9]
	s_waitcnt lgkmcnt(9)
	v_mfma_f32_16x16x32_bf16 v[2:5], v[10:13], v[188:191], v[2:5]
	s_waitcnt lgkmcnt(7)
	v_mfma_f32_16x16x32_bf16 v[6:9], v[192:195], v[246:249], v[6:9]
	s_waitcnt lgkmcnt(6)
	v_mfma_f32_16x16x32_bf16 v[2:5], v[192:195], v[204:207], v[2:5]
	ds_read_b128 v[10:13], v14 offset:32768
	ds_read_b128 v[184:187], v15 offset:32768
	ds_read_b128 v[188:191], v15 offset:36864
	ds_read_b128 v[192:195], v224 offset:32768
	ds_read_b128 v[204:207], v225 offset:32768
	ds_read_b128 v[246:249], v225 offset:36864
	s_waitcnt lgkmcnt(10)
	v_mfma_f32_16x16x32_bf16 v[6:9], v[196:199], v[200:203], v[6:9]
	s_waitcnt lgkmcnt(9)
	v_mfma_f32_16x16x32_bf16 v[2:5], v[196:199], v[226:229], v[2:5]
	s_waitcnt lgkmcnt(7)
	v_mfma_f32_16x16x32_bf16 v[6:9], v[230:233], v[234:237], v[6:9]
	s_waitcnt lgkmcnt(6)
	v_mfma_f32_16x16x32_bf16 v[2:5], v[230:233], v[242:245], v[2:5]
	ds_read_b128 v[196:199], v238 offset:32768
	ds_read_b128 v[200:203], v239 offset:32768
	ds_read_b128 v[226:229], v239 offset:36864
	ds_read_b128 v[230:233], v240 offset:32768
	ds_read_b128 v[234:237], v0 offset:32768
	ds_read_b128 v[242:245], v0 offset:36864
	s_waitcnt lgkmcnt(10)
	v_mfma_f32_16x16x32_bf16 v[6:9], v[10:13], v[184:187], v[6:9]
	s_waitcnt lgkmcnt(9)
	v_mfma_f32_16x16x32_bf16 v[2:5], v[10:13], v[188:191], v[2:5]
	s_waitcnt lgkmcnt(7)
	v_mfma_f32_16x16x32_bf16 v[6:9], v[192:195], v[204:207], v[6:9]
	s_waitcnt lgkmcnt(6)
	v_mfma_f32_16x16x32_bf16 v[2:5], v[192:195], v[246:249], v[2:5]
	ds_read_b128 v[10:13], v14 offset:49152
	ds_read_b128 v[184:187], v15 offset:49152
	ds_read_b128 v[188:191], v15 offset:53248
	ds_read_b128 v[192:195], v224 offset:49152
	ds_read_b128 v[204:207], v225 offset:49152
	ds_read_b128 v[246:249], v225 offset:53248
	s_waitcnt lgkmcnt(10)
	v_mfma_f32_16x16x32_bf16 v[6:9], v[196:199], v[200:203], v[6:9]
	s_waitcnt lgkmcnt(9)
	v_mfma_f32_16x16x32_bf16 v[2:5], v[196:199], v[226:229], v[2:5]
	s_waitcnt lgkmcnt(7)
	v_mfma_f32_16x16x32_bf16 v[6:9], v[230:233], v[234:237], v[6:9]
	s_waitcnt lgkmcnt(6)
	v_mfma_f32_16x16x32_bf16 v[2:5], v[230:233], v[242:245], v[2:5]
	ds_read_b128 v[196:199], v238 offset:49152
	ds_read_b128 v[200:203], v239 offset:49152
	ds_read_b128 v[226:229], v239 offset:53248
	ds_read_b128 v[230:233], v240 offset:49152
	ds_read_b128 v[234:237], v0 offset:49152
	ds_read_b128 v[242:245], v0 offset:53248
	s_waitcnt lgkmcnt(10)
	v_mfma_f32_16x16x32_bf16 v[6:9], v[10:13], v[184:187], v[6:9]
	s_waitcnt lgkmcnt(9)
	v_mfma_f32_16x16x32_bf16 v[2:5], v[10:13], v[188:191], v[2:5]
	s_waitcnt lgkmcnt(7)
	v_mfma_f32_16x16x32_bf16 v[6:9], v[192:195], v[204:207], v[6:9]
	s_waitcnt lgkmcnt(6)
	v_mfma_f32_16x16x32_bf16 v[2:5], v[192:195], v[246:249], v[2:5]
	ds_read_b128 v[10:13], v221
	ds_read_b128 v[184:187], v222
	s_waitcnt lgkmcnt(6)
	v_mfma_f32_16x16x32_bf16 v[6:9], v[196:199], v[200:203], v[6:9]
	s_waitcnt lgkmcnt(5)
	v_mfma_f32_16x16x32_bf16 v[2:5], v[196:199], v[226:229], v[2:5]
	s_waitcnt lgkmcnt(3)
	v_mfma_f32_16x16x32_bf16 v[6:9], v[230:233], v[234:237], v[6:9]
	s_waitcnt lgkmcnt(2)
	v_mfma_f32_16x16x32_bf16 v[2:5], v[230:233], v[242:245], v[2:5]
	s_waitcnt lgkmcnt(0)
	v_mfma_f32_16x16x32_bf16 v[6:9], v[184:187], v[80:83], v[6:9]
	s_and_b64 vcc, exec, s[6:7]
	v_mfma_f32_16x16x32_bf16 v[2:5], v[184:187], v[88:91], v[2:5]
	v_mfma_f32_16x16x32_bf16 v[6:9], v[10:13], v[84:87], v[6:9]
	v_mfma_f32_16x16x32_bf16 v[2:5], v[10:13], v[92:95], v[2:5]
	s_nop 6
	ds_write_b128 v214, v[6:9]
	ds_write_b128 v214, v[2:5] offset:4352
	s_waitcnt lgkmcnt(0)
	s_barrier
	s_cbranch_vccnz .LBB0_1565
	s_cmp_gt_u32 s46, 62
	s_cselect_b64 s[6:7], -1, 0
	s_waitcnt vmcnt(3)
	v_mov_b64_e32 v[126:127], v[102:103]
	s_waitcnt vmcnt(2)
	v_mov_b64_e32 v[138:139], v[114:115]
	s_waitcnt vmcnt(1)
	v_mov_b64_e32 v[150:151], v[142:143]
	s_waitcnt vmcnt(0)
	v_mov_b64_e32 v[162:163], v[154:155]
	s_and_b64 vcc, exec, s[6:7]
	v_mov_b64_e32 v[124:125], v[100:101]
	v_mov_b64_e32 v[136:137], v[112:113]
	v_mov_b64_e32 v[148:149], v[140:141]
	v_mov_b64_e32 v[160:161], v[152:153]
	s_cbranch_vccnz .LBB0_1561
	v_cvt_pk_bf16_f32 v124, v100, v101
	v_cvt_pk_bf16_f32 v125, v102, v103
	v_cvt_pk_bf16_f32 v126, v96, v97
	v_cvt_pk_bf16_f32 v127, v98, v99
	v_cvt_pk_bf16_f32 v136, v112, v113
	v_cvt_pk_bf16_f32 v137, v114, v115
	v_cvt_pk_bf16_f32 v138, v108, v109
	v_cvt_pk_bf16_f32 v139, v110, v111
	v_cvt_pk_bf16_f32 v148, v140, v141
	v_cvt_pk_bf16_f32 v149, v142, v143
	v_cvt_pk_bf16_f32 v150, v120, v121
	v_cvt_pk_bf16_f32 v151, v122, v123
	v_cvt_pk_bf16_f32 v160, v152, v153
	v_cvt_pk_bf16_f32 v161, v154, v155
	v_cvt_pk_bf16_f32 v162, v132, v133
	v_cvt_pk_bf16_f32 v163, v134, v135

.LBB0_1563:
	s_andn2_b64 vcc, exec, s[2:3]
	s_cbranch_vccnz .LBB0_1565
	v_lshlrev_b32_e32 v0, 2, v2
	v_and_b32_e32 v0, 28, v0
	s_movk_i32 s2, 0xffc0
	v_and_or_b32 v0, v3, s2, v0
	v_lshlrev_b32_e32 v6, 5, v2
	s_add_u32 s2, s47, s14
	v_add_u32_e32 v2, 0x10000, v6
	v_mov_b32_e32 v3, v1
	s_addc_u32 s3, s48, s15
	v_lshl_add_u64 v[2:3], s[2:3], 0, v[2:3]
	v_lshl_add_u64 v[4:5], v[2:3], 0, s[76:77]
	v_add_co_u32_e32 v2, vcc, s84, v2
	s_nop 1
	v_addc_co_u32_e32 v3, vcc, 0, v3, vcc
	global_load_dwordx4 v[164:167], v[2:3], off
	global_load_dwordx4 v[104:107], v[4:5], off offset:16
	v_add_u32_e32 v2, 0x14000, v6
	v_mov_b32_e32 v3, v1
	v_lshl_add_u64 v[2:3], s[2:3], 0, v[2:3]
	v_lshl_add_u64 v[4:5], v[2:3], 0, s[76:77]
	v_add_co_u32_e32 v2, vcc, s84, v2
	s_nop 1
	v_addc_co_u32_e32 v3, vcc, 0, v3, vcc
	global_load_dwordx4 v[168:171], v[2:3], off
	global_load_dwordx4 v[116:119], v[4:5], off offset:16
	v_add_u32_e32 v2, 0x18000, v6
	v_mov_b32_e32 v3, v1
	v_lshl_add_u64 v[2:3], s[2:3], 0, v[2:3]
	v_lshl_add_u64 v[4:5], v[2:3], 0, s[76:77]
	v_add_co_u32_e32 v2, vcc, s84, v2
	s_nop 1
	v_addc_co_u32_e32 v3, vcc, 0, v3, vcc
	global_load_dwordx4 v[172:175], v[2:3], off
	global_load_dwordx4 v[128:131], v[4:5], off offset:16
	v_add_u32_e32 v2, 0x1c000, v6
	v_mov_b32_e32 v3, v1
	v_lshl_add_u64 v[2:3], s[2:3], 0, v[2:3]
	v_lshl_add_u64 v[4:5], v[2:3], 0, s[76:77]
	v_add_co_u32_e32 v2, vcc, 0x20000, v2
	s_nop 1
	v_addc_co_u32_e32 v3, vcc, 0, v3, vcc
	global_load_dwordx4 v[176:179], v[2:3], off
	global_load_dwordx4 v[144:147], v[4:5], off offset:16
	v_lshl_add_u64 v[2:3], v[0:1], 2, s[18:19]
	global_load_dwordx4 v[180:183], v[2:3], off offset:-128
	global_load_dwordx4 v[156:159], v[2:3], off
	s_cmp_eq_u32 s46, 62
	s_cbranch_scc1 .Lsa_ld1_bf16
	v_mov_b32_e32 v0, v210
	s_add_u32 s2, s47, s14
	v_lshlrev_b32_e32 v0, 5, v0
	s_addc_u32 s3, s48, s15
	s_add_u32 s2, s2, 0x20000
	s_addc_u32 s3, s3, 0
	v_lshl_add_u64 v[2:3], s[2:3], 0, v[0:1]
	v_lshl_add_u64 v[4:5], v[2:3], 0, s[76:77]
	v_add_co_u32_e32 v2, vcc, 0x20000, v2
	s_nop 1
	v_addc_co_u32_e32 v3, vcc, 0, v3, vcc
	global_load_dwordx4 v[100:103], v[2:3], off
	global_load_dwordx4 v[96:99], v[4:5], off offset:16
	v_add_u32_e32 v2, 0x4000, v0
	v_mov_b32_e32 v3, v1
	v_lshl_add_u64 v[2:3], s[2:3], 0, v[2:3]
	v_lshl_add_u64 v[4:5], v[2:3], 0, s[76:77]
	v_add_co_u32_e32 v2, vcc, s84, v2
	s_nop 1
	v_addc_co_u32_e32 v3, vcc, 0, v3, vcc
	global_load_dwordx4 v[112:115], v[2:3], off
	global_load_dwordx4 v[108:111], v[4:5], off offset:16
	v_add_u32_e32 v2, 0x8000, v0
	v_mov_b32_e32 v3, v1
	v_lshl_add_u64 v[2:3], s[2:3], 0, v[2:3]
	v_lshl_add_u64 v[4:5], v[2:3], 0, s[76:77]
	v_add_co_u32_e32 v2, vcc, s84, v2
	v_add_u32_e32 v0, 0xc000, v0
	s_nop 0
	v_addc_co_u32_e32 v3, vcc, 0, v3, vcc
	global_load_dwordx4 v[140:143], v[2:3], off
	global_load_dwordx4 v[120:123], v[4:5], off offset:16
	v_lshl_add_u64 v[2:3], s[2:3], 0, v[0:1]
	v_lshl_add_u64 v[4:5], v[2:3], 0, s[76:77]
	v_add_co_u32_e32 v2, vcc, 0x20000, v2
	s_nop 1
	v_addc_co_u32_e32 v3, vcc, 0, v3, vcc
	global_load_dwordx4 v[152:155], v[2:3], off
	global_load_dwordx4 v[132:135], v[4:5], off offset:16
	s_branch .LBB0_1565
.Lsa_ld1_bf16:
	v_mov_b32_e32 v6, v210
	s_nop 0
	v_lshlrev_b32_e32 v0, 3, v6
	v_and_b32_e32 v0, 0x1f8, v0
	v_lshrrev_b32_e32 v2, 6, v6
	v_add_u32_e32 v4, 0x200, v6
	v_mad_u64_u32 v[2:3], s[2:3], v2, s90, v[0:1]
	v_lshrrev_b32_e32 v4, 6, v4
	v_mov_b32_e32 v3, v1
	v_mad_u64_u32 v[4:5], s[2:3], v4, s90, v[0:1]
	v_lshl_add_u64 v[2:3], v[2:3], 1, s[16:17]
	v_mov_b32_e32 v5, v1
	v_lshl_add_u64 v[4:5], v[4:5], 1, s[16:17]
	global_load_dwordx4 v[100:103], v[2:3], off
	global_load_dwordx4 v[112:115], v[4:5], off
	v_add_u32_e32 v2, 0x400, v6
	v_lshrrev_b32_e32 v2, 6, v2
	v_add_u32_e32 v4, 0x600, v6
	v_mad_u64_u32 v[2:3], s[2:3], v2, s90, v[0:1]
	v_lshrrev_b32_e32 v4, 6, v4
	v_mov_b32_e32 v3, v1
	v_mad_u64_u32 v[4:5], s[2:3], v4, s90, v[0:1]
	v_lshl_add_u64 v[2:3], v[2:3], 1, s[16:17]
	v_mov_b32_e32 v5, v1
	v_lshl_add_u64 v[4:5], v[4:5], 1, s[16:17]
	global_load_dwordx4 v[140:143], v[2:3], off
	global_load_dwordx4 v[152:155], v[4:5], off
